# multi-tile GEMM K-loops: first iteration after an epilogue waits vmcnt(24) in its first two segments (store drain deferred two MFMA segments); on top of early-MFMA k=4
# speedup vs baseline: 1.0021x; 1.0021x over previous
.LBB0_202:
	s_add_u32 s2, s6, 0xfffc0080
	s_addc_u32 s3, s7, -1
	s_add_i32 s66, 0, 0x10000
	s_cmp_eq_u32 s89, 12
	s_cselect_b32 s57, s20, s3
	s_cselect_b32 s56, s21, s2
	v_add_u32_e32 v148, s66, v151
	s_cselect_b32 s91, s49, s88
	s_cselect_b32 s90, s51, s62
	s_add_i32 s2, 0, 0x14000
	ds_read_b128 v[144:147], v148
	ds_read_b128 v[164:167], v148 offset:1024
	ds_read_b128 v[176:179], v148 offset:2048
	ds_read_b128 v[180:183], v148 offset:3072
	v_add_u32_e32 v148, s2, v151
	ds_read_b128 v[184:187], v148
	ds_read_b128 v[188:191], v148 offset:1024
	ds_read_b128 v[192:195], v148 offset:2048
	ds_read_b128 v[196:199], v148 offset:3072
	v_lshl_add_u64 v[148:149], s[6:7], 0, v[140:141]
	s_add_i32 m0, s17, 0xc000
	ds_read_b128 v[200:203], v153
	ds_read_b128 v[204:207], v153 offset:1024
	ds_read_b128 v[208:211], v153 offset:2048
	ds_read_b128 v[212:215], v153 offset:3072
	ds_read_b128 v[216:219], v153 offset:4096
	ds_read_b128 v[220:223], v153 offset:5120
	ds_read_b128 v[224:227], v153 offset:6144
	ds_read_b128 v[228:231], v153 offset:7168
	global_load_lds_dwordx4 v[148:149], off
	v_lshl_add_u64 v[148:149], s[6:7], 0, v[142:143]
	s_add_i32 m0, s17, 0xe000
	s_nop 0
	global_load_lds_dwordx4 v[148:149], off
	s_cmp_lg_u32 s89, -2
	s_cbranch_scc1 .Lrw_g10_std
	s_cmp_lt_u32 s87, 2
	s_cbranch_scc1 .Lrw_g10_std
	s_waitcnt vmcnt(24)
	s_branch .Lrw_g10_done
.Lrw_g10_std:
	s_waitcnt vmcnt(8)
.Lrw_g10_done:
	s_waitcnt lgkmcnt(0)
	v_mfma_f32_16x16x32_f16 v[128:131], v[144:147], v[200:203], v[128:131]
	v_mfma_f32_16x16x32_f16 v[124:127], v[176:179], v[200:203], v[124:127]
	v_mfma_f32_16x16x32_f16 v[112:115], v[144:147], v[208:211], v[112:115]
	v_mfma_f32_16x16x32_f16 v[108:111], v[176:179], v[208:211], v[108:111]
	s_barrier
	s_setprio 1
	s_waitcnt lgkmcnt(0)
	v_mfma_f32_16x16x32_f16 v[96:99], v[144:147], v[216:219], v[96:99]
	v_mfma_f32_16x16x32_f16 v[92:95], v[176:179], v[216:219], v[92:95]
	v_mfma_f32_16x16x32_f16 v[80:83], v[144:147], v[224:227], v[80:83]
	v_mfma_f32_16x16x32_f16 v[76:79], v[176:179], v[224:227], v[76:79]
	v_mfma_f32_16x16x32_f16 v[128:131], v[164:167], v[204:207], v[128:131]
	v_mfma_f32_16x16x32_f16 v[124:127], v[180:183], v[204:207], v[124:127]
	v_mfma_f32_16x16x32_f16 v[112:115], v[164:167], v[212:215], v[112:115]
	v_mfma_f32_16x16x32_f16 v[108:111], v[180:183], v[212:215], v[108:111]
	v_mfma_f32_16x16x32_f16 v[96:99], v[164:167], v[220:223], v[96:99]
	v_mfma_f32_16x16x32_f16 v[92:95], v[180:183], v[220:223], v[92:95]
	v_mfma_f32_16x16x32_f16 v[80:83], v[164:167], v[228:231], v[80:83]
	v_mfma_f32_16x16x32_f16 v[76:79], v[180:183], v[228:231], v[76:79]
	s_setprio 0
	s_setprio 1
	v_mfma_f32_16x16x32_f16 v[120:123], v[184:187], v[200:203], v[120:123]
	v_mfma_f32_16x16x32_f16 v[116:119], v[192:195], v[200:203], v[116:119]
	v_mfma_f32_16x16x32_f16 v[104:107], v[184:187], v[208:211], v[104:107]
	v_mfma_f32_16x16x32_f16 v[100:103], v[192:195], v[208:211], v[100:103]
	v_mfma_f32_16x16x32_f16 v[88:91], v[184:187], v[216:219], v[88:91]
	v_mfma_f32_16x16x32_f16 v[84:87], v[192:195], v[216:219], v[84:87]
	v_mfma_f32_16x16x32_f16 v[72:75], v[184:187], v[224:227], v[72:75]
	v_mfma_f32_16x16x32_f16 v[68:71], v[192:195], v[224:227], v[68:71]
	v_mfma_f32_16x16x32_f16 v[120:123], v[188:191], v[204:207], v[120:123]
	v_mfma_f32_16x16x32_f16 v[116:119], v[196:199], v[204:207], v[116:119]
	v_mfma_f32_16x16x32_f16 v[104:107], v[188:191], v[212:215], v[104:107]
	v_mfma_f32_16x16x32_f16 v[100:103], v[196:199], v[212:215], v[100:103]
	v_mfma_f32_16x16x32_f16 v[88:91], v[188:191], v[220:223], v[88:91]
	v_mfma_f32_16x16x32_f16 v[84:87], v[196:199], v[220:223], v[84:87]
	v_mfma_f32_16x16x32_f16 v[72:75], v[188:191], v[228:231], v[72:75]
	v_mfma_f32_16x16x32_f16 v[68:71], v[196:199], v[228:231], v[68:71]
	s_setprio 0
	s_barrier
	s_add_i32 s3, s66, s16
	v_lshl_add_u64 v[148:149], s[90:91], 0, v[2:3]
	s_mov_b32 m0, s3
	ds_read_b128 v[200:203], v153 offset:16384
	ds_read_b128 v[204:207], v153 offset:17408
	ds_read_b128 v[208:211], v153 offset:18432
	ds_read_b128 v[212:215], v153 offset:19456
	ds_read_b128 v[216:219], v153 offset:20480
	ds_read_b128 v[220:223], v153 offset:21504
	ds_read_b128 v[224:227], v153 offset:22528
	ds_read_b128 v[228:231], v153 offset:23552
	global_load_lds_dwordx4 v[148:149], off
	v_lshl_add_u64 v[154:155], s[90:91], 0, v[0:1]
	s_add_i32 m0, s3, 0x2000
	s_add_i32 s2, s2, s16
	global_load_lds_dwordx4 v[154:155], off
	v_lshl_add_u64 v[232:233], s[90:91], 0, v[136:137]
	s_mov_b32 m0, s2
	v_lshl_add_u64 v[234:235], s[90:91], 0, v[132:133]
	global_load_lds_dwordx4 v[232:233], off
	s_add_i32 m0, s2, 0x2000
	v_lshl_add_u64 v[236:237], s[56:57], 0, v[138:139]
	global_load_lds_dwordx4 v[234:235], off
	s_mov_b32 m0, s17
	v_lshl_add_u64 v[238:239], s[56:57], 0, v[134:135]
	global_load_lds_dwordx4 v[236:237], off
	s_mov_b32 m0, s28
	s_nop 0
	global_load_lds_dwordx4 v[238:239], off
	s_cmp_lg_u32 s89, -2
	s_cbranch_scc1 .Lrw_g11_std
	s_cmp_lt_u32 s87, 2
	s_cbranch_scc1 .Lrw_g11_std
	s_waitcnt vmcnt(24)
	s_branch .Lrw_g11_done

.Lrw_g11_done:
	s_waitcnt lgkmcnt(0)
	v_mfma_f32_16x16x32_f16 v[64:67], v[144:147], v[200:203], v[64:67]
	v_mfma_f32_16x16x32_f16 v[60:63], v[176:179], v[200:203], v[60:63]
	v_mfma_f32_16x16x32_f16 v[48:51], v[144:147], v[208:211], v[48:51]
	v_mfma_f32_16x16x32_f16 v[44:47], v[176:179], v[208:211], v[44:47]
	s_barrier
	s_setprio 1
	s_waitcnt lgkmcnt(0)
	v_mfma_f32_16x16x32_f16 v[32:35], v[144:147], v[216:219], v[32:35]
	v_mfma_f32_16x16x32_f16 v[28:31], v[176:179], v[216:219], v[28:31]
	v_mfma_f32_16x16x32_f16 v[16:19], v[144:147], v[224:227], v[16:19]
	v_mfma_f32_16x16x32_f16 v[12:15], v[176:179], v[224:227], v[12:15]
	v_mfma_f32_16x16x32_f16 v[64:67], v[164:167], v[204:207], v[64:67]
	v_mfma_f32_16x16x32_f16 v[60:63], v[180:183], v[204:207], v[60:63]
	v_mfma_f32_16x16x32_f16 v[48:51], v[164:167], v[212:215], v[48:51]
	v_mfma_f32_16x16x32_f16 v[44:47], v[180:183], v[212:215], v[44:47]
	v_mfma_f32_16x16x32_f16 v[32:35], v[164:167], v[220:223], v[32:35]
	v_mfma_f32_16x16x32_f16 v[28:31], v[180:183], v[220:223], v[28:31]
	v_mfma_f32_16x16x32_f16 v[16:19], v[164:167], v[228:231], v[16:19]
	v_mfma_f32_16x16x32_f16 v[12:15], v[180:183], v[228:231], v[12:15]
	s_setprio 0
	s_setprio 1
	v_mfma_f32_16x16x32_f16 v[56:59], v[184:187], v[200:203], v[56:59]
	v_mfma_f32_16x16x32_f16 v[52:55], v[192:195], v[200:203], v[52:55]
	v_mfma_f32_16x16x32_f16 v[40:43], v[184:187], v[208:211], v[40:43]
	v_mfma_f32_16x16x32_f16 v[36:39], v[192:195], v[208:211], v[36:39]
	v_mfma_f32_16x16x32_f16 v[24:27], v[184:187], v[216:219], v[24:27]
	v_mfma_f32_16x16x32_f16 v[20:23], v[192:195], v[216:219], v[20:23]
	v_mfma_f32_16x16x32_f16 v[8:11], v[184:187], v[224:227], v[8:11]
	v_mfma_f32_16x16x32_f16 v[4:7], v[192:195], v[224:227], v[4:7]
	v_mfma_f32_16x16x32_f16 v[56:59], v[188:191], v[204:207], v[56:59]
	v_mfma_f32_16x16x32_f16 v[52:55], v[196:199], v[204:207], v[52:55]
	v_mfma_f32_16x16x32_f16 v[40:43], v[188:191], v[212:215], v[40:43]
	v_mfma_f32_16x16x32_f16 v[36:39], v[196:199], v[212:215], v[36:39]
	v_mfma_f32_16x16x32_f16 v[24:27], v[188:191], v[220:223], v[24:27]
	v_mfma_f32_16x16x32_f16 v[20:23], v[196:199], v[220:223], v[20:23]
	v_mfma_f32_16x16x32_f16 v[8:11], v[188:191], v[228:231], v[8:11]
	v_mfma_f32_16x16x32_f16 v[4:7], v[196:199], v[228:231], v[4:7]
	s_setprio 0
	s_barrier
	s_add_i32 s2, 0, 0x18000
	s_add_i32 s3, 0, 0x1c000
	v_add_u32_e32 v180, s2, v151
	v_add_u32_e32 v196, s3, v151
	ds_read_b128 v[144:147], v180
	ds_read_b128 v[164:167], v180 offset:1024
	ds_read_b128 v[176:179], v180 offset:2048
	ds_read_b128 v[180:183], v180 offset:3072
	ds_read_b128 v[184:187], v196
	ds_read_b128 v[188:191], v196 offset:1024
	ds_read_b128 v[192:195], v196 offset:2048
	ds_read_b128 v[196:199], v196 offset:3072
	s_add_u32 s56, s56, 0x40000
	s_addc_u32 s57, s57, 0
	s_mov_b32 m0, s58
	v_lshl_add_u64 v[240:241], s[56:57], 0, v[138:139]
	ds_read_b128 v[200:203], v153 offset:32768
	ds_read_b128 v[204:207], v153 offset:33792
	ds_read_b128 v[208:211], v153 offset:34816
	ds_read_b128 v[212:215], v153 offset:35840
	ds_read_b128 v[216:219], v153 offset:36864
	ds_read_b128 v[220:223], v153 offset:37888
	ds_read_b128 v[224:227], v153 offset:38912
	ds_read_b128 v[228:231], v153 offset:39936
	global_load_lds_dwordx4 v[240:241], off
	v_lshl_add_u64 v[240:241], s[56:57], 0, v[134:135]
	s_mov_b32 m0, s59
	s_nop 0
	global_load_lds_dwordx4 v[240:241], off
	s_waitcnt vmcnt(8)
	s_waitcnt lgkmcnt(0)
	v_mfma_f32_16x16x32_f16 v[128:131], v[144:147], v[200:203], v[128:131]
	v_mfma_f32_16x16x32_f16 v[124:127], v[176:179], v[200:203], v[124:127]
	v_mfma_f32_16x16x32_f16 v[112:115], v[144:147], v[208:211], v[112:115]
	v_mfma_f32_16x16x32_f16 v[108:111], v[176:179], v[208:211], v[108:111]
	s_barrier
	s_setprio 1
	s_waitcnt lgkmcnt(0)
	v_mfma_f32_16x16x32_f16 v[96:99], v[144:147], v[216:219], v[96:99]
	v_mfma_f32_16x16x32_f16 v[92:95], v[176:179], v[216:219], v[92:95]
	v_mfma_f32_16x16x32_f16 v[80:83], v[144:147], v[224:227], v[80:83]
	v_mfma_f32_16x16x32_f16 v[76:79], v[176:179], v[224:227], v[76:79]
	v_mfma_f32_16x16x32_f16 v[128:131], v[164:167], v[204:207], v[128:131]
	v_mfma_f32_16x16x32_f16 v[124:127], v[180:183], v[204:207], v[124:127]
	v_mfma_f32_16x16x32_f16 v[112:115], v[164:167], v[212:215], v[112:115]
	v_mfma_f32_16x16x32_f16 v[108:111], v[180:183], v[212:215], v[108:111]
	v_mfma_f32_16x16x32_f16 v[96:99], v[164:167], v[220:223], v[96:99]
	v_mfma_f32_16x16x32_f16 v[92:95], v[180:183], v[220:223], v[92:95]
	v_mfma_f32_16x16x32_f16 v[80:83], v[164:167], v[228:231], v[80:83]
	v_mfma_f32_16x16x32_f16 v[76:79], v[180:183], v[228:231], v[76:79]
	s_setprio 0
	s_setprio 1
	v_mfma_f32_16x16x32_f16 v[120:123], v[184:187], v[200:203], v[120:123]
	v_mfma_f32_16x16x32_f16 v[116:119], v[192:195], v[200:203], v[116:119]
	v_mfma_f32_16x16x32_f16 v[104:107], v[184:187], v[208:211], v[104:107]
	v_mfma_f32_16x16x32_f16 v[100:103], v[192:195], v[208:211], v[100:103]
	v_mfma_f32_16x16x32_f16 v[88:91], v[184:187], v[216:219], v[88:91]
	v_mfma_f32_16x16x32_f16 v[84:87], v[192:195], v[216:219], v[84:87]
	v_mfma_f32_16x16x32_f16 v[72:75], v[184:187], v[224:227], v[72:75]
	v_mfma_f32_16x16x32_f16 v[68:71], v[192:195], v[224:227], v[68:71]
	v_mfma_f32_16x16x32_f16 v[120:123], v[188:191], v[204:207], v[120:123]
	v_mfma_f32_16x16x32_f16 v[116:119], v[196:199], v[204:207], v[116:119]
	v_mfma_f32_16x16x32_f16 v[104:107], v[188:191], v[212:215], v[104:107]
	v_mfma_f32_16x16x32_f16 v[100:103], v[196:199], v[212:215], v[100:103]
	v_mfma_f32_16x16x32_f16 v[88:91], v[188:191], v[220:223], v[88:91]
	v_mfma_f32_16x16x32_f16 v[84:87], v[196:199], v[220:223], v[84:87]
	v_mfma_f32_16x16x32_f16 v[72:75], v[188:191], v[228:231], v[72:75]
	v_mfma_f32_16x16x32_f16 v[68:71], v[196:199], v[228:231], v[68:71]
	s_setprio 0
	s_barrier
	s_add_i32 s2, s2, s16
	v_lshl_add_u64 v[148:149], v[148:149], 0, s[82:83]
	s_mov_b32 m0, s2
	ds_read_b128 v[200:203], v153 offset:49152
	ds_read_b128 v[204:207], v153 offset:50176
	ds_read_b128 v[208:211], v153 offset:51200
	ds_read_b128 v[212:215], v153 offset:52224
	ds_read_b128 v[216:219], v153 offset:53248
	ds_read_b128 v[220:223], v153 offset:54272
	ds_read_b128 v[224:227], v153 offset:55296
	ds_read_b128 v[228:231], v153 offset:56320
	global_load_lds_dwordx4 v[148:149], off
	v_lshl_add_u64 v[148:149], v[154:155], 0, s[82:83]
	s_add_i32 m0, s2, 0x2000
	s_add_i32 s2, s3, s16
	global_load_lds_dwordx4 v[148:149], off
	v_lshl_add_u64 v[148:149], v[232:233], 0, s[82:83]
	s_mov_b32 m0, s2
	s_nop 0
	global_load_lds_dwordx4 v[148:149], off
	v_lshl_add_u64 v[148:149], v[234:235], 0, s[82:83]
	s_add_i32 m0, s2, 0x2000
	s_nop 0
	global_load_lds_dwordx4 v[148:149], off
	v_lshl_add_u64 v[148:149], v[236:237], 0, s[82:83]
	s_mov_b32 m0, s60
	s_nop 0
	global_load_lds_dwordx4 v[148:149], off
	v_lshl_add_u64 v[148:149], v[238:239], 0, s[82:83]
	s_mov_b32 m0, s61
	s_nop 0
	global_load_lds_dwordx4 v[148:149], off
	s_waitcnt vmcnt(8)
	s_waitcnt lgkmcnt(0)
	v_mfma_f32_16x16x32_f16 v[64:67], v[144:147], v[200:203], v[64:67]
	v_mfma_f32_16x16x32_f16 v[60:63], v[176:179], v[200:203], v[60:63]
	v_mfma_f32_16x16x32_f16 v[48:51], v[144:147], v[208:211], v[48:51]
	v_mfma_f32_16x16x32_f16 v[44:47], v[176:179], v[208:211], v[44:47]
	s_barrier
	s_setprio 1
	s_waitcnt lgkmcnt(0)
	v_mfma_f32_16x16x32_f16 v[32:35], v[144:147], v[216:219], v[32:35]
	v_mfma_f32_16x16x32_f16 v[28:31], v[176:179], v[216:219], v[28:31]
	v_mfma_f32_16x16x32_f16 v[16:19], v[144:147], v[224:227], v[16:19]
	v_mfma_f32_16x16x32_f16 v[12:15], v[176:179], v[224:227], v[12:15]
	v_mfma_f32_16x16x32_f16 v[64:67], v[164:167], v[204:207], v[64:67]
	v_mfma_f32_16x16x32_f16 v[60:63], v[180:183], v[204:207], v[60:63]
	v_mfma_f32_16x16x32_f16 v[48:51], v[164:167], v[212:215], v[48:51]
	v_mfma_f32_16x16x32_f16 v[44:47], v[180:183], v[212:215], v[44:47]
	v_mfma_f32_16x16x32_f16 v[32:35], v[164:167], v[220:223], v[32:35]
	v_mfma_f32_16x16x32_f16 v[28:31], v[180:183], v[220:223], v[28:31]
	v_mfma_f32_16x16x32_f16 v[16:19], v[164:167], v[228:231], v[16:19]
	v_mfma_f32_16x16x32_f16 v[12:15], v[180:183], v[228:231], v[12:15]
	s_setprio 0
	s_setprio 1
	v_mfma_f32_16x16x32_f16 v[56:59], v[184:187], v[200:203], v[56:59]
	v_mfma_f32_16x16x32_f16 v[52:55], v[192:195], v[200:203], v[52:55]
	v_mfma_f32_16x16x32_f16 v[40:43], v[184:187], v[208:211], v[40:43]
	v_mfma_f32_16x16x32_f16 v[36:39], v[192:195], v[208:211], v[36:39]
	v_mfma_f32_16x16x32_f16 v[24:27], v[184:187], v[216:219], v[24:27]
	v_mfma_f32_16x16x32_f16 v[20:23], v[192:195], v[216:219], v[20:23]
	v_mfma_f32_16x16x32_f16 v[8:11], v[184:187], v[224:227], v[8:11]
	v_mfma_f32_16x16x32_f16 v[4:7], v[192:195], v[224:227], v[4:7]
	v_mfma_f32_16x16x32_f16 v[56:59], v[188:191], v[204:207], v[56:59]
	v_mfma_f32_16x16x32_f16 v[52:55], v[196:199], v[204:207], v[52:55]
	v_mfma_f32_16x16x32_f16 v[40:43], v[188:191], v[212:215], v[40:43]
	v_mfma_f32_16x16x32_f16 v[36:39], v[196:199], v[212:215], v[36:39]
	v_mfma_f32_16x16x32_f16 v[24:27], v[188:191], v[220:223], v[24:27]
	v_mfma_f32_16x16x32_f16 v[20:23], v[196:199], v[220:223], v[20:23]
	v_mfma_f32_16x16x32_f16 v[8:11], v[188:191], v[228:231], v[8:11]
	v_mfma_f32_16x16x32_f16 v[4:7], v[196:199], v[228:231], v[4:7]
	s_setprio 0
	s_barrier
	s_add_i32 s89, s89, 2
	s_add_u32 s6, s6, 0x100
	s_addc_u32 s7, s7, 0
	s_add_u32 s62, s62, 0x100
	s_addc_u32 s88, s88, 0
	s_cmp_gt_u32 s89, 13
	s_cbranch_scc0 .LBB0_202
	s_and_b64 vcc, exec, s[46:47]
	s_cbranch_vccz .LBB0_205
	s_barrier

.LBB0_589:
	ds_read_b128 v[156:159], v152
	ds_read_b128 v[160:163], v152 offset:1024
	ds_read_b128 v[164:167], v152 offset:2048
	ds_read_b128 v[172:175], v152 offset:3072
	ds_read_b128 v[176:179], v153
	ds_read_b128 v[180:183], v153 offset:1024
	ds_read_b128 v[184:187], v153 offset:2048
	ds_read_b128 v[188:191], v153 offset:3072
	s_add_u32 s2, s44, 0xfffc0080
	s_addc_u32 s3, s45, -1
	s_cmp_eq_u32 s54, 12
	s_cselect_b32 s47, s25, s3
	s_cselect_b32 s46, s50, s2
	s_cselect_b32 s57, s19, s53
	s_cselect_b32 s56, s51, s52
	v_lshl_add_u64 v[168:169], s[44:45], 0, v[142:143]
	s_add_i32 m0, s14, 0xc000
	ds_read_b128 v[192:195], v154
	ds_read_b128 v[196:199], v154 offset:1024
	ds_read_b128 v[200:203], v154 offset:2048
	ds_read_b128 v[204:207], v154 offset:3072
	ds_read_b128 v[208:211], v154 offset:4096
	ds_read_b128 v[212:215], v154 offset:5120
	ds_read_b128 v[216:219], v154 offset:6144
	ds_read_b128 v[220:223], v154 offset:7168
	global_load_lds_dwordx4 v[168:169], off
	v_lshl_add_u64 v[168:169], s[44:45], 0, v[144:145]
	s_add_i32 m0, s14, 0xe000
	s_nop 0
	global_load_lds_dwordx4 v[168:169], off
	s_cmp_lg_u32 s54, -2
	s_cbranch_scc1 .Lrw_kk0_std
	s_cmp_lt_u32 s27, 2
	s_cbranch_scc1 .Lrw_kk0_std
	s_waitcnt vmcnt(24)
	s_branch .Lrw_kk0_done

.Lrw_kk0_done:
	s_waitcnt lgkmcnt(0)
	v_mfma_f32_16x16x32_f16 v[124:127], v[156:159], v[192:195], v[124:127]
	v_mfma_f32_16x16x32_f16 v[120:123], v[164:167], v[192:195], v[120:123]
	v_mfma_f32_16x16x32_f16 v[116:119], v[156:159], v[200:203], v[116:119]
	v_mfma_f32_16x16x32_f16 v[108:111], v[164:167], v[200:203], v[108:111]
	s_barrier
	s_setprio 1
	s_waitcnt lgkmcnt(0)
	v_mfma_f32_16x16x32_f16 v[100:103], v[156:159], v[208:211], v[100:103]
	v_mfma_f32_16x16x32_f16 v[92:95], v[164:167], v[208:211], v[92:95]
	v_mfma_f32_16x16x32_f16 v[84:87], v[156:159], v[216:219], v[84:87]
	v_mfma_f32_16x16x32_f16 v[76:79], v[164:167], v[216:219], v[76:79]
	v_mfma_f32_16x16x32_f16 v[124:127], v[160:163], v[196:199], v[124:127]
	v_mfma_f32_16x16x32_f16 v[120:123], v[172:175], v[196:199], v[120:123]
	v_mfma_f32_16x16x32_f16 v[116:119], v[160:163], v[204:207], v[116:119]
	v_mfma_f32_16x16x32_f16 v[108:111], v[172:175], v[204:207], v[108:111]
	v_mfma_f32_16x16x32_f16 v[100:103], v[160:163], v[212:215], v[100:103]
	v_mfma_f32_16x16x32_f16 v[92:95], v[172:175], v[212:215], v[92:95]
	v_mfma_f32_16x16x32_f16 v[84:87], v[160:163], v[220:223], v[84:87]
	v_mfma_f32_16x16x32_f16 v[76:79], v[172:175], v[220:223], v[76:79]
	s_setprio 0
	s_setprio 1
	v_mfma_f32_16x16x32_f16 v[112:115], v[176:179], v[192:195], v[112:115]
	v_mfma_f32_16x16x32_f16 v[104:107], v[184:187], v[192:195], v[104:107]
	v_mfma_f32_16x16x32_f16 v[96:99], v[176:179], v[200:203], v[96:99]
	v_mfma_f32_16x16x32_f16 v[88:91], v[184:187], v[200:203], v[88:91]
	v_mfma_f32_16x16x32_f16 v[80:83], v[176:179], v[208:211], v[80:83]
	v_mfma_f32_16x16x32_f16 v[72:75], v[184:187], v[208:211], v[72:75]
	v_mfma_f32_16x16x32_f16 v[68:71], v[176:179], v[216:219], v[68:71]
	v_mfma_f32_16x16x32_f16 v[64:67], v[184:187], v[216:219], v[64:67]
	v_mfma_f32_16x16x32_f16 v[112:115], v[180:183], v[196:199], v[112:115]
	v_mfma_f32_16x16x32_f16 v[104:107], v[188:191], v[196:199], v[104:107]
	v_mfma_f32_16x16x32_f16 v[96:99], v[180:183], v[204:207], v[96:99]
	v_mfma_f32_16x16x32_f16 v[88:91], v[188:191], v[204:207], v[88:91]
	v_mfma_f32_16x16x32_f16 v[80:83], v[180:183], v[212:215], v[80:83]
	v_mfma_f32_16x16x32_f16 v[72:75], v[188:191], v[212:215], v[72:75]
	v_mfma_f32_16x16x32_f16 v[68:71], v[180:183], v[220:223], v[68:71]
	v_mfma_f32_16x16x32_f16 v[64:67], v[188:191], v[220:223], v[64:67]
	s_setprio 0
	s_barrier
	s_add_i32 s2, s29, s12
	v_lshl_add_u64 v[168:169], s[56:57], 0, v[134:135]
	s_mov_b32 m0, s2
	ds_read_b128 v[192:195], v154 offset:16384
	ds_read_b128 v[196:199], v154 offset:17408
	ds_read_b128 v[200:203], v154 offset:18432
	ds_read_b128 v[204:207], v154 offset:19456
	ds_read_b128 v[208:211], v154 offset:20480
	ds_read_b128 v[212:215], v154 offset:21504
	ds_read_b128 v[216:219], v154 offset:22528
	ds_read_b128 v[220:223], v154 offset:23552
	global_load_lds_dwordx4 v[168:169], off
	v_lshl_add_u64 v[224:225], s[56:57], 0, v[128:129]
	s_add_i32 m0, s2, 0x2000
	s_add_i32 s2, s48, s12
	global_load_lds_dwordx4 v[224:225], off
	v_lshl_add_u64 v[226:227], s[56:57], 0, v[136:137]
	s_mov_b32 m0, s2
	v_lshl_add_u64 v[228:229], s[56:57], 0, v[130:131]
	global_load_lds_dwordx4 v[226:227], off
	s_add_i32 m0, s2, 0x2000
	v_lshl_add_u64 v[230:231], s[46:47], 0, v[138:139]
	global_load_lds_dwordx4 v[228:229], off
	s_mov_b32 m0, s14
	v_lshl_add_u64 v[232:233], s[46:47], 0, v[132:133]
	global_load_lds_dwordx4 v[230:231], off
	s_mov_b32 m0, s15
	s_nop 0
	global_load_lds_dwordx4 v[232:233], off
	s_cmp_lg_u32 s54, -2
	s_cbranch_scc1 .Lrw_kk1_std
	s_cmp_lt_u32 s27, 2
	s_cbranch_scc1 .Lrw_kk1_std
	s_waitcnt vmcnt(24)
	s_branch .Lrw_kk1_done

.Lrw_kk1_done:
	s_waitcnt lgkmcnt(0)
	v_mfma_f32_16x16x32_f16 v[60:63], v[156:159], v[192:195], v[60:63]
	v_mfma_f32_16x16x32_f16 v[56:59], v[164:167], v[192:195], v[56:59]
	v_mfma_f32_16x16x32_f16 v[52:55], v[156:159], v[200:203], v[52:55]
	v_mfma_f32_16x16x32_f16 v[44:47], v[164:167], v[200:203], v[44:47]
	s_barrier
	s_setprio 1
	s_waitcnt lgkmcnt(0)
	v_mfma_f32_16x16x32_f16 v[36:39], v[156:159], v[208:211], v[36:39]
	v_mfma_f32_16x16x32_f16 v[28:31], v[164:167], v[208:211], v[28:31]
	v_mfma_f32_16x16x32_f16 v[20:23], v[156:159], v[216:219], v[20:23]
	v_mfma_f32_16x16x32_f16 v[12:15], v[164:167], v[216:219], v[12:15]
	v_mfma_f32_16x16x32_f16 v[60:63], v[160:163], v[196:199], v[60:63]
	v_mfma_f32_16x16x32_f16 v[56:59], v[172:175], v[196:199], v[56:59]
	v_mfma_f32_16x16x32_f16 v[52:55], v[160:163], v[204:207], v[52:55]
	v_mfma_f32_16x16x32_f16 v[44:47], v[172:175], v[204:207], v[44:47]
	v_mfma_f32_16x16x32_f16 v[36:39], v[160:163], v[212:215], v[36:39]
	v_mfma_f32_16x16x32_f16 v[28:31], v[172:175], v[212:215], v[28:31]
	v_mfma_f32_16x16x32_f16 v[20:23], v[160:163], v[220:223], v[20:23]
	v_mfma_f32_16x16x32_f16 v[12:15], v[172:175], v[220:223], v[12:15]
	s_setprio 0
	s_setprio 1
	v_mfma_f32_16x16x32_f16 v[48:51], v[176:179], v[192:195], v[48:51]
	v_mfma_f32_16x16x32_f16 v[40:43], v[184:187], v[192:195], v[40:43]
	v_mfma_f32_16x16x32_f16 v[32:35], v[176:179], v[200:203], v[32:35]
	v_mfma_f32_16x16x32_f16 v[24:27], v[184:187], v[200:203], v[24:27]
	v_mfma_f32_16x16x32_f16 v[16:19], v[176:179], v[208:211], v[16:19]
	v_mfma_f32_16x16x32_f16 v[8:11], v[184:187], v[208:211], v[8:11]
	v_mfma_f32_16x16x32_f16 v[4:7], v[176:179], v[216:219], v[4:7]
	v_mfma_f32_16x16x32_f16 v[0:3], v[184:187], v[216:219], v[0:3]
	v_mfma_f32_16x16x32_f16 v[48:51], v[180:183], v[196:199], v[48:51]
	v_mfma_f32_16x16x32_f16 v[40:43], v[188:191], v[196:199], v[40:43]
	v_mfma_f32_16x16x32_f16 v[32:35], v[180:183], v[204:207], v[32:35]
	v_mfma_f32_16x16x32_f16 v[24:27], v[188:191], v[204:207], v[24:27]
	v_mfma_f32_16x16x32_f16 v[16:19], v[180:183], v[212:215], v[16:19]
	v_mfma_f32_16x16x32_f16 v[8:11], v[188:191], v[212:215], v[8:11]
	v_mfma_f32_16x16x32_f16 v[4:7], v[180:183], v[220:223], v[4:7]
	v_mfma_f32_16x16x32_f16 v[0:3], v[188:191], v[220:223], v[0:3]
	s_setprio 0
	s_barrier
	s_add_i32 s2, 0, 0x18000
	s_add_i32 s3, 0, 0x1c000
	v_add_u32_e32 v172, s2, v151
	v_add_u32_e32 v188, s3, v151
	ds_read_b128 v[156:159], v172
	ds_read_b128 v[160:163], v172 offset:1024
	ds_read_b128 v[164:167], v172 offset:2048
	ds_read_b128 v[172:175], v172 offset:3072
	ds_read_b128 v[176:179], v188
	ds_read_b128 v[180:183], v188 offset:1024
	ds_read_b128 v[184:187], v188 offset:2048
	ds_read_b128 v[188:191], v188 offset:3072
	s_add_u32 s46, s46, 0x40000
	s_addc_u32 s47, s47, 0
	s_mov_b32 m0, s16
	v_lshl_add_u64 v[234:235], s[46:47], 0, v[138:139]
	ds_read_b128 v[192:195], v154 offset:32768
	ds_read_b128 v[196:199], v154 offset:33792
	ds_read_b128 v[200:203], v154 offset:34816
	ds_read_b128 v[204:207], v154 offset:35840
	ds_read_b128 v[208:211], v154 offset:36864
	ds_read_b128 v[212:215], v154 offset:37888
	ds_read_b128 v[216:219], v154 offset:38912
	ds_read_b128 v[220:223], v154 offset:39936
	global_load_lds_dwordx4 v[234:235], off
	v_lshl_add_u64 v[234:235], s[46:47], 0, v[132:133]
	s_mov_b32 m0, s17
	s_nop 0
	global_load_lds_dwordx4 v[234:235], off
	s_waitcnt vmcnt(8)
	s_waitcnt lgkmcnt(0)
	v_mfma_f32_16x16x32_f16 v[124:127], v[156:159], v[192:195], v[124:127]
	v_mfma_f32_16x16x32_f16 v[120:123], v[164:167], v[192:195], v[120:123]
	v_mfma_f32_16x16x32_f16 v[116:119], v[156:159], v[200:203], v[116:119]
	v_mfma_f32_16x16x32_f16 v[108:111], v[164:167], v[200:203], v[108:111]
	s_barrier
	s_setprio 1
	s_waitcnt lgkmcnt(0)
	v_mfma_f32_16x16x32_f16 v[100:103], v[156:159], v[208:211], v[100:103]
	v_mfma_f32_16x16x32_f16 v[92:95], v[164:167], v[208:211], v[92:95]
	v_mfma_f32_16x16x32_f16 v[84:87], v[156:159], v[216:219], v[84:87]
	v_mfma_f32_16x16x32_f16 v[76:79], v[164:167], v[216:219], v[76:79]
	v_mfma_f32_16x16x32_f16 v[124:127], v[160:163], v[196:199], v[124:127]
	v_mfma_f32_16x16x32_f16 v[120:123], v[172:175], v[196:199], v[120:123]
	v_mfma_f32_16x16x32_f16 v[116:119], v[160:163], v[204:207], v[116:119]
	v_mfma_f32_16x16x32_f16 v[108:111], v[172:175], v[204:207], v[108:111]
	v_mfma_f32_16x16x32_f16 v[100:103], v[160:163], v[212:215], v[100:103]
	v_mfma_f32_16x16x32_f16 v[92:95], v[172:175], v[212:215], v[92:95]
	v_mfma_f32_16x16x32_f16 v[84:87], v[160:163], v[220:223], v[84:87]
	v_mfma_f32_16x16x32_f16 v[76:79], v[172:175], v[220:223], v[76:79]
	s_setprio 0
	s_setprio 1
	v_mfma_f32_16x16x32_f16 v[112:115], v[176:179], v[192:195], v[112:115]
	v_mfma_f32_16x16x32_f16 v[104:107], v[184:187], v[192:195], v[104:107]
	v_mfma_f32_16x16x32_f16 v[96:99], v[176:179], v[200:203], v[96:99]
	v_mfma_f32_16x16x32_f16 v[88:91], v[184:187], v[200:203], v[88:91]
	v_mfma_f32_16x16x32_f16 v[80:83], v[176:179], v[208:211], v[80:83]
	v_mfma_f32_16x16x32_f16 v[72:75], v[184:187], v[208:211], v[72:75]
	v_mfma_f32_16x16x32_f16 v[68:71], v[176:179], v[216:219], v[68:71]
	v_mfma_f32_16x16x32_f16 v[64:67], v[184:187], v[216:219], v[64:67]
	v_mfma_f32_16x16x32_f16 v[112:115], v[180:183], v[196:199], v[112:115]
	v_mfma_f32_16x16x32_f16 v[104:107], v[188:191], v[196:199], v[104:107]
	v_mfma_f32_16x16x32_f16 v[96:99], v[180:183], v[204:207], v[96:99]
	v_mfma_f32_16x16x32_f16 v[88:91], v[188:191], v[204:207], v[88:91]
	v_mfma_f32_16x16x32_f16 v[80:83], v[180:183], v[212:215], v[80:83]
	v_mfma_f32_16x16x32_f16 v[72:75], v[188:191], v[212:215], v[72:75]
	v_mfma_f32_16x16x32_f16 v[68:71], v[180:183], v[220:223], v[68:71]
	v_mfma_f32_16x16x32_f16 v[64:67], v[188:191], v[220:223], v[64:67]
	s_setprio 0
	s_barrier
	s_add_i32 s2, s2, s12
	v_lshl_add_u64 v[168:169], v[168:169], 0, s[6:7]
	s_mov_b32 m0, s2
	ds_read_b128 v[192:195], v154 offset:49152
	ds_read_b128 v[196:199], v154 offset:50176
	ds_read_b128 v[200:203], v154 offset:51200
	ds_read_b128 v[204:207], v154 offset:52224
	ds_read_b128 v[208:211], v154 offset:53248
	ds_read_b128 v[212:215], v154 offset:54272
	ds_read_b128 v[216:219], v154 offset:55296
	ds_read_b128 v[220:223], v154 offset:56320
	global_load_lds_dwordx4 v[168:169], off
	v_lshl_add_u64 v[168:169], v[224:225], 0, s[6:7]
	s_add_i32 m0, s2, 0x2000
	s_add_i32 s2, s3, s12
	global_load_lds_dwordx4 v[168:169], off
	v_lshl_add_u64 v[168:169], v[226:227], 0, s[6:7]
	s_mov_b32 m0, s2
	s_nop 0
	global_load_lds_dwordx4 v[168:169], off
	v_lshl_add_u64 v[168:169], v[228:229], 0, s[6:7]
	s_add_i32 m0, s2, 0x2000
	s_nop 0
	global_load_lds_dwordx4 v[168:169], off
	v_lshl_add_u64 v[168:169], v[230:231], 0, s[6:7]
	s_mov_b32 m0, s20
	s_nop 0
	global_load_lds_dwordx4 v[168:169], off
	v_lshl_add_u64 v[168:169], v[232:233], 0, s[6:7]
	s_mov_b32 m0, s21
	s_nop 0
	global_load_lds_dwordx4 v[168:169], off
	s_waitcnt vmcnt(8)
	s_waitcnt lgkmcnt(0)
	v_mfma_f32_16x16x32_f16 v[60:63], v[156:159], v[192:195], v[60:63]
	v_mfma_f32_16x16x32_f16 v[56:59], v[164:167], v[192:195], v[56:59]
	v_mfma_f32_16x16x32_f16 v[52:55], v[156:159], v[200:203], v[52:55]
	v_mfma_f32_16x16x32_f16 v[44:47], v[164:167], v[200:203], v[44:47]
	s_barrier
	s_setprio 1
	s_waitcnt lgkmcnt(0)
	v_mfma_f32_16x16x32_f16 v[36:39], v[156:159], v[208:211], v[36:39]
	v_mfma_f32_16x16x32_f16 v[28:31], v[164:167], v[208:211], v[28:31]
	v_mfma_f32_16x16x32_f16 v[20:23], v[156:159], v[216:219], v[20:23]
	v_mfma_f32_16x16x32_f16 v[12:15], v[164:167], v[216:219], v[12:15]
	v_mfma_f32_16x16x32_f16 v[60:63], v[160:163], v[196:199], v[60:63]
	v_mfma_f32_16x16x32_f16 v[56:59], v[172:175], v[196:199], v[56:59]
	v_mfma_f32_16x16x32_f16 v[52:55], v[160:163], v[204:207], v[52:55]
	v_mfma_f32_16x16x32_f16 v[44:47], v[172:175], v[204:207], v[44:47]
	v_mfma_f32_16x16x32_f16 v[36:39], v[160:163], v[212:215], v[36:39]
	v_mfma_f32_16x16x32_f16 v[28:31], v[172:175], v[212:215], v[28:31]
	v_mfma_f32_16x16x32_f16 v[20:23], v[160:163], v[220:223], v[20:23]
	v_mfma_f32_16x16x32_f16 v[12:15], v[172:175], v[220:223], v[12:15]
	s_setprio 0
	s_setprio 1
	v_mfma_f32_16x16x32_f16 v[48:51], v[176:179], v[192:195], v[48:51]
	v_mfma_f32_16x16x32_f16 v[40:43], v[184:187], v[192:195], v[40:43]
	v_mfma_f32_16x16x32_f16 v[32:35], v[176:179], v[200:203], v[32:35]
	v_mfma_f32_16x16x32_f16 v[24:27], v[184:187], v[200:203], v[24:27]
	v_mfma_f32_16x16x32_f16 v[16:19], v[176:179], v[208:211], v[16:19]
	v_mfma_f32_16x16x32_f16 v[8:11], v[184:187], v[208:211], v[8:11]
	v_mfma_f32_16x16x32_f16 v[4:7], v[176:179], v[216:219], v[4:7]
	v_mfma_f32_16x16x32_f16 v[0:3], v[184:187], v[216:219], v[0:3]
	v_mfma_f32_16x16x32_f16 v[48:51], v[180:183], v[196:199], v[48:51]
	v_mfma_f32_16x16x32_f16 v[40:43], v[188:191], v[196:199], v[40:43]
	v_mfma_f32_16x16x32_f16 v[32:35], v[180:183], v[204:207], v[32:35]
	v_mfma_f32_16x16x32_f16 v[24:27], v[188:191], v[204:207], v[24:27]
	v_mfma_f32_16x16x32_f16 v[16:19], v[180:183], v[212:215], v[16:19]
	v_mfma_f32_16x16x32_f16 v[8:11], v[188:191], v[212:215], v[8:11]
	v_mfma_f32_16x16x32_f16 v[4:7], v[180:183], v[220:223], v[4:7]
	v_mfma_f32_16x16x32_f16 v[0:3], v[188:191], v[220:223], v[0:3]
	s_setprio 0
	s_barrier
	s_add_i32 s54, s54, 2
	s_add_u32 s44, s44, 0x100
	s_addc_u32 s45, s45, 0
	s_add_u32 s52, s52, 0x100
	s_addc_u32 s53, s53, 0
	s_cmp_gt_u32 s54, 13
	s_cbranch_scc0 .LBB0_589
	s_and_b64 vcc, exec, s[8:9]
	s_cbranch_vccz .LBB0_592
	s_barrier

.LBB0_673:
	s_add_u32 s23, s54, 0xfffc0080
	s_addc_u32 s24, s55, -1
	s_add_i32 s26, 0, 0x10000
	s_cmp_eq_u32 s21, 12
	s_cselect_b32 s57, s15, s24
	s_cselect_b32 s56, s16, s23
	v_add_u32_e32 v149, s26, v147
	s_cselect_b32 s25, s17, s20
	s_cselect_b32 s24, s18, s19
	s_add_i32 s23, 0, 0x14000
	ds_read_b128 v[150:153], v149
	ds_read_b128 v[184:187], v149 offset:1024
	ds_read_b128 v[188:191], v149 offset:2048
	ds_read_b128 v[192:195], v149 offset:3072
	v_add_u32_e32 v149, s23, v147
	ds_read_b128 v[196:199], v149
	ds_read_b128 v[200:203], v149 offset:1024
	ds_read_b128 v[204:207], v149 offset:2048
	ds_read_b128 v[208:211], v149 offset:3072
	v_lshl_add_u64 v[154:155], s[54:55], 0, v[142:143]
	s_add_i32 m0, s1, 0xc000
	ds_read_b128 v[212:215], v148
	ds_read_b128 v[216:219], v148 offset:1024
	ds_read_b128 v[220:223], v148 offset:2048
	ds_read_b128 v[224:227], v148 offset:3072
	ds_read_b128 v[228:231], v148 offset:4096
	ds_read_b128 v[232:235], v148 offset:5120
	ds_read_b128 v[236:239], v148 offset:6144
	ds_read_b128 v[240:243], v148 offset:7168
	global_load_lds_dwordx4 v[154:155], off
	v_lshl_add_u64 v[154:155], s[54:55], 0, v[144:145]
	s_add_i32 m0, s1, 0xe000
	s_nop 0
	global_load_lds_dwordx4 v[154:155], off
	s_cmp_lg_u32 s21, -2
	s_cbranch_scc1 .Lrw_qg0_std
	s_cmp_lt_u32 s12, 2
	s_cbranch_scc1 .Lrw_qg0_std
	s_waitcnt vmcnt(24)
	s_branch .Lrw_qg0_done

.Lrw_qg0_done:
	s_waitcnt lgkmcnt(0)
	v_mfma_f32_16x16x32_f16 v[128:131], v[150:153], v[212:215], v[128:131]
	v_mfma_f32_16x16x32_f16 v[124:127], v[188:191], v[212:215], v[124:127]
	v_mfma_f32_16x16x32_f16 v[120:123], v[150:153], v[220:223], v[120:123]
	v_mfma_f32_16x16x32_f16 v[112:115], v[188:191], v[220:223], v[112:115]
	s_barrier
	s_setprio 1
	s_waitcnt lgkmcnt(0)
	v_mfma_f32_16x16x32_f16 v[104:107], v[150:153], v[228:231], v[104:107]
	v_mfma_f32_16x16x32_f16 v[100:103], v[188:191], v[228:231], v[100:103]
	v_mfma_f32_16x16x32_f16 v[88:91], v[150:153], v[236:239], v[88:91]
	v_mfma_f32_16x16x32_f16 v[84:87], v[188:191], v[236:239], v[84:87]
	v_mfma_f32_16x16x32_f16 v[128:131], v[184:187], v[216:219], v[128:131]
	v_mfma_f32_16x16x32_f16 v[124:127], v[192:195], v[216:219], v[124:127]
	v_mfma_f32_16x16x32_f16 v[120:123], v[184:187], v[224:227], v[120:123]
	v_mfma_f32_16x16x32_f16 v[112:115], v[192:195], v[224:227], v[112:115]
	v_mfma_f32_16x16x32_f16 v[104:107], v[184:187], v[232:235], v[104:107]
	v_mfma_f32_16x16x32_f16 v[100:103], v[192:195], v[232:235], v[100:103]
	v_mfma_f32_16x16x32_f16 v[88:91], v[184:187], v[240:243], v[88:91]
	v_mfma_f32_16x16x32_f16 v[84:87], v[192:195], v[240:243], v[84:87]
	s_setprio 0
	s_setprio 1
	v_mfma_f32_16x16x32_f16 v[116:119], v[196:199], v[212:215], v[116:119]
	v_mfma_f32_16x16x32_f16 v[108:111], v[204:207], v[212:215], v[108:111]
	v_mfma_f32_16x16x32_f16 v[96:99], v[196:199], v[220:223], v[96:99]
	v_mfma_f32_16x16x32_f16 v[92:95], v[204:207], v[220:223], v[92:95]
	v_mfma_f32_16x16x32_f16 v[80:83], v[196:199], v[228:231], v[80:83]
	v_mfma_f32_16x16x32_f16 v[76:79], v[204:207], v[228:231], v[76:79]
	v_mfma_f32_16x16x32_f16 v[72:75], v[196:199], v[236:239], v[72:75]
	v_mfma_f32_16x16x32_f16 v[68:71], v[204:207], v[236:239], v[68:71]
	v_mfma_f32_16x16x32_f16 v[116:119], v[200:203], v[216:219], v[116:119]
	v_mfma_f32_16x16x32_f16 v[108:111], v[208:211], v[216:219], v[108:111]
	v_mfma_f32_16x16x32_f16 v[96:99], v[200:203], v[224:227], v[96:99]
	v_mfma_f32_16x16x32_f16 v[92:95], v[208:211], v[224:227], v[92:95]
	v_mfma_f32_16x16x32_f16 v[80:83], v[200:203], v[232:235], v[80:83]
	v_mfma_f32_16x16x32_f16 v[76:79], v[208:211], v[232:235], v[76:79]
	v_mfma_f32_16x16x32_f16 v[72:75], v[200:203], v[240:243], v[72:75]
	v_mfma_f32_16x16x32_f16 v[68:71], v[208:211], v[240:243], v[68:71]
	s_setprio 0
	s_barrier
	s_add_i32 s26, s26, s0
	v_lshl_add_u64 v[154:155], s[24:25], 0, v[136:137]
	s_mov_b32 m0, s26
	ds_read_b128 v[212:215], v148 offset:16384
	ds_read_b128 v[216:219], v148 offset:17408
	ds_read_b128 v[220:223], v148 offset:18432
	ds_read_b128 v[224:227], v148 offset:19456
	ds_read_b128 v[228:231], v148 offset:20480
	ds_read_b128 v[232:235], v148 offset:21504
	ds_read_b128 v[236:239], v148 offset:22528
	ds_read_b128 v[240:243], v148 offset:23552
	global_load_lds_dwordx4 v[154:155], off
	v_lshl_add_u64 v[168:169], s[24:25], 0, v[0:1]
	s_add_i32 m0, s26, 0x2000
	s_add_i32 s23, s23, s0
	global_load_lds_dwordx4 v[168:169], off
	v_lshl_add_u64 v[244:245], s[24:25], 0, v[138:139]
	s_mov_b32 m0, s23
	v_lshl_add_u64 v[246:247], s[24:25], 0, v[132:133]
	global_load_lds_dwordx4 v[244:245], off
	s_add_i32 m0, s23, 0x2000
	v_lshl_add_u64 v[248:249], s[56:57], 0, v[140:141]
	global_load_lds_dwordx4 v[246:247], off
	s_mov_b32 m0, s1
	v_lshl_add_u64 v[250:251], s[56:57], 0, v[134:135]
	global_load_lds_dwordx4 v[248:249], off
	s_mov_b32 m0, s2
	s_nop 0
	global_load_lds_dwordx4 v[250:251], off
	s_cmp_lg_u32 s21, -2
	s_cbranch_scc1 .Lrw_qg1_std
	s_cmp_lt_u32 s12, 2
	s_cbranch_scc1 .Lrw_qg1_std
	s_waitcnt vmcnt(24)
	s_branch .Lrw_qg1_done

.Lrw_qg1_done:
	s_waitcnt lgkmcnt(0)
	v_mfma_f32_16x16x32_f16 v[64:67], v[150:153], v[212:215], v[64:67]
	v_mfma_f32_16x16x32_f16 v[60:63], v[188:191], v[212:215], v[60:63]
	v_mfma_f32_16x16x32_f16 v[56:59], v[150:153], v[220:223], v[56:59]
	v_mfma_f32_16x16x32_f16 v[52:55], v[188:191], v[220:223], v[52:55]
	s_barrier
	s_setprio 1
	s_waitcnt lgkmcnt(0)
	v_mfma_f32_16x16x32_f16 v[40:43], v[150:153], v[228:231], v[40:43]
	v_mfma_f32_16x16x32_f16 v[36:39], v[188:191], v[228:231], v[36:39]
	v_mfma_f32_16x16x32_f16 v[24:27], v[150:153], v[236:239], v[24:27]
	v_mfma_f32_16x16x32_f16 v[20:23], v[188:191], v[236:239], v[20:23]
	v_mfma_f32_16x16x32_f16 v[64:67], v[184:187], v[216:219], v[64:67]
	v_mfma_f32_16x16x32_f16 v[60:63], v[192:195], v[216:219], v[60:63]
	v_mfma_f32_16x16x32_f16 v[56:59], v[184:187], v[224:227], v[56:59]
	v_mfma_f32_16x16x32_f16 v[52:55], v[192:195], v[224:227], v[52:55]
	v_mfma_f32_16x16x32_f16 v[40:43], v[184:187], v[232:235], v[40:43]
	v_mfma_f32_16x16x32_f16 v[36:39], v[192:195], v[232:235], v[36:39]
	v_mfma_f32_16x16x32_f16 v[24:27], v[184:187], v[240:243], v[24:27]
	v_mfma_f32_16x16x32_f16 v[20:23], v[192:195], v[240:243], v[20:23]
	s_setprio 0
	s_setprio 1
	v_mfma_f32_16x16x32_f16 v[48:51], v[196:199], v[212:215], v[48:51]
	v_mfma_f32_16x16x32_f16 v[44:47], v[204:207], v[212:215], v[44:47]
	v_mfma_f32_16x16x32_f16 v[32:35], v[196:199], v[220:223], v[32:35]
	v_mfma_f32_16x16x32_f16 v[28:31], v[204:207], v[220:223], v[28:31]
	v_mfma_f32_16x16x32_f16 v[16:19], v[196:199], v[228:231], v[16:19]
	v_mfma_f32_16x16x32_f16 v[12:15], v[204:207], v[228:231], v[12:15]
	v_mfma_f32_16x16x32_f16 v[8:11], v[196:199], v[236:239], v[8:11]
	v_mfma_f32_16x16x32_f16 v[4:7], v[204:207], v[236:239], v[4:7]
	v_mfma_f32_16x16x32_f16 v[48:51], v[200:203], v[216:219], v[48:51]
	v_mfma_f32_16x16x32_f16 v[44:47], v[208:211], v[216:219], v[44:47]
	v_mfma_f32_16x16x32_f16 v[32:35], v[200:203], v[224:227], v[32:35]
	v_mfma_f32_16x16x32_f16 v[28:31], v[208:211], v[224:227], v[28:31]
	v_mfma_f32_16x16x32_f16 v[16:19], v[200:203], v[232:235], v[16:19]
	v_mfma_f32_16x16x32_f16 v[12:15], v[208:211], v[232:235], v[12:15]
	v_mfma_f32_16x16x32_f16 v[8:11], v[200:203], v[240:243], v[8:11]
	v_mfma_f32_16x16x32_f16 v[4:7], v[208:211], v[240:243], v[4:7]
	s_setprio 0
	s_barrier
	s_add_i32 s23, 0, 0x18000
	v_add_u32_e32 v149, s23, v147
	s_add_i32 s26, 0, 0x1c000
	ds_read_b128 v[150:153], v149
	ds_read_b128 v[184:187], v149 offset:1024
	ds_read_b128 v[188:191], v149 offset:2048
	ds_read_b128 v[192:195], v149 offset:3072
	v_add_u32_e32 v149, s26, v147
	ds_read_b128 v[196:199], v149
	ds_read_b128 v[200:203], v149 offset:1024
	ds_read_b128 v[204:207], v149 offset:2048
	ds_read_b128 v[208:211], v149 offset:3072
	s_add_u32 s24, s56, 0x40000
	s_addc_u32 s25, s57, 0
	s_mov_b32 m0, s3
	v_lshl_add_u64 v[178:179], s[24:25], 0, v[140:141]
	ds_read_b128 v[212:215], v148 offset:32768
	ds_read_b128 v[216:219], v148 offset:33792
	ds_read_b128 v[220:223], v148 offset:34816
	ds_read_b128 v[224:227], v148 offset:35840
	ds_read_b128 v[228:231], v148 offset:36864
	ds_read_b128 v[232:235], v148 offset:37888
	ds_read_b128 v[236:239], v148 offset:38912
	ds_read_b128 v[240:243], v148 offset:39936
	global_load_lds_dwordx4 v[178:179], off
	v_lshl_add_u64 v[178:179], s[24:25], 0, v[134:135]
	s_mov_b32 m0, s4
	s_nop 0
	global_load_lds_dwordx4 v[178:179], off
	s_waitcnt vmcnt(8)
	s_waitcnt lgkmcnt(0)
	v_mfma_f32_16x16x32_f16 v[128:131], v[150:153], v[212:215], v[128:131]
	v_mfma_f32_16x16x32_f16 v[124:127], v[188:191], v[212:215], v[124:127]
	v_mfma_f32_16x16x32_f16 v[120:123], v[150:153], v[220:223], v[120:123]
	v_mfma_f32_16x16x32_f16 v[112:115], v[188:191], v[220:223], v[112:115]
	s_barrier
	s_setprio 1
	s_waitcnt lgkmcnt(0)
	v_mfma_f32_16x16x32_f16 v[104:107], v[150:153], v[228:231], v[104:107]
	v_mfma_f32_16x16x32_f16 v[100:103], v[188:191], v[228:231], v[100:103]
	v_mfma_f32_16x16x32_f16 v[88:91], v[150:153], v[236:239], v[88:91]
	v_mfma_f32_16x16x32_f16 v[84:87], v[188:191], v[236:239], v[84:87]
	v_mfma_f32_16x16x32_f16 v[128:131], v[184:187], v[216:219], v[128:131]
	v_mfma_f32_16x16x32_f16 v[124:127], v[192:195], v[216:219], v[124:127]
	v_mfma_f32_16x16x32_f16 v[120:123], v[184:187], v[224:227], v[120:123]
	v_mfma_f32_16x16x32_f16 v[112:115], v[192:195], v[224:227], v[112:115]
	v_mfma_f32_16x16x32_f16 v[104:107], v[184:187], v[232:235], v[104:107]
	v_mfma_f32_16x16x32_f16 v[100:103], v[192:195], v[232:235], v[100:103]
	v_mfma_f32_16x16x32_f16 v[88:91], v[184:187], v[240:243], v[88:91]
	v_mfma_f32_16x16x32_f16 v[84:87], v[192:195], v[240:243], v[84:87]
	s_setprio 0
	s_setprio 1
	v_mfma_f32_16x16x32_f16 v[116:119], v[196:199], v[212:215], v[116:119]
	v_mfma_f32_16x16x32_f16 v[108:111], v[204:207], v[212:215], v[108:111]
	v_mfma_f32_16x16x32_f16 v[96:99], v[196:199], v[220:223], v[96:99]
	v_mfma_f32_16x16x32_f16 v[92:95], v[204:207], v[220:223], v[92:95]
	v_mfma_f32_16x16x32_f16 v[80:83], v[196:199], v[228:231], v[80:83]
	v_mfma_f32_16x16x32_f16 v[76:79], v[204:207], v[228:231], v[76:79]
	v_mfma_f32_16x16x32_f16 v[72:75], v[196:199], v[236:239], v[72:75]
	v_mfma_f32_16x16x32_f16 v[68:71], v[204:207], v[236:239], v[68:71]
	v_mfma_f32_16x16x32_f16 v[116:119], v[200:203], v[216:219], v[116:119]
	v_mfma_f32_16x16x32_f16 v[108:111], v[208:211], v[216:219], v[108:111]
	v_mfma_f32_16x16x32_f16 v[96:99], v[200:203], v[224:227], v[96:99]
	v_mfma_f32_16x16x32_f16 v[92:95], v[208:211], v[224:227], v[92:95]
	v_mfma_f32_16x16x32_f16 v[80:83], v[200:203], v[232:235], v[80:83]
	v_mfma_f32_16x16x32_f16 v[76:79], v[208:211], v[232:235], v[76:79]
	v_mfma_f32_16x16x32_f16 v[72:75], v[200:203], v[240:243], v[72:75]
	v_mfma_f32_16x16x32_f16 v[68:71], v[208:211], v[240:243], v[68:71]
	s_setprio 0
	s_barrier
	s_add_i32 s23, s23, s0
	v_lshl_add_u64 v[154:155], v[154:155], 0, s[72:73]
	s_mov_b32 m0, s23
	ds_read_b128 v[212:215], v148 offset:49152
	ds_read_b128 v[216:219], v148 offset:50176
	ds_read_b128 v[220:223], v148 offset:51200
	ds_read_b128 v[224:227], v148 offset:52224
	ds_read_b128 v[228:231], v148 offset:53248
	ds_read_b128 v[232:235], v148 offset:54272
	ds_read_b128 v[236:239], v148 offset:55296
	ds_read_b128 v[240:243], v148 offset:56320
	global_load_lds_dwordx4 v[154:155], off
	v_lshl_add_u64 v[154:155], v[168:169], 0, s[72:73]
	s_add_i32 m0, s23, 0x2000
	s_add_i32 s23, s26, s0
	global_load_lds_dwordx4 v[154:155], off
	v_lshl_add_u64 v[154:155], v[244:245], 0, s[72:73]
	s_mov_b32 m0, s23
	s_nop 0
	global_load_lds_dwordx4 v[154:155], off
	v_lshl_add_u64 v[154:155], v[246:247], 0, s[72:73]
	s_add_i32 m0, s23, 0x2000
	s_nop 0
	global_load_lds_dwordx4 v[154:155], off
	v_lshl_add_u64 v[154:155], v[248:249], 0, s[72:73]
	s_mov_b32 m0, s10
	s_nop 0
	global_load_lds_dwordx4 v[154:155], off
	v_lshl_add_u64 v[154:155], v[250:251], 0, s[72:73]
	s_mov_b32 m0, s11
	s_nop 0
	global_load_lds_dwordx4 v[154:155], off
	s_waitcnt vmcnt(8)
	s_waitcnt lgkmcnt(0)
	v_mfma_f32_16x16x32_f16 v[64:67], v[150:153], v[212:215], v[64:67]
	v_mfma_f32_16x16x32_f16 v[60:63], v[188:191], v[212:215], v[60:63]
	v_mfma_f32_16x16x32_f16 v[56:59], v[150:153], v[220:223], v[56:59]
	v_mfma_f32_16x16x32_f16 v[52:55], v[188:191], v[220:223], v[52:55]
	s_barrier
	s_setprio 1
	s_waitcnt lgkmcnt(0)
	v_mfma_f32_16x16x32_f16 v[40:43], v[150:153], v[228:231], v[40:43]
	v_mfma_f32_16x16x32_f16 v[36:39], v[188:191], v[228:231], v[36:39]
	v_mfma_f32_16x16x32_f16 v[24:27], v[150:153], v[236:239], v[24:27]
	v_mfma_f32_16x16x32_f16 v[20:23], v[188:191], v[236:239], v[20:23]
	v_mfma_f32_16x16x32_f16 v[64:67], v[184:187], v[216:219], v[64:67]
	v_mfma_f32_16x16x32_f16 v[60:63], v[192:195], v[216:219], v[60:63]
	v_mfma_f32_16x16x32_f16 v[56:59], v[184:187], v[224:227], v[56:59]
	v_mfma_f32_16x16x32_f16 v[52:55], v[192:195], v[224:227], v[52:55]
	v_mfma_f32_16x16x32_f16 v[40:43], v[184:187], v[232:235], v[40:43]
	v_mfma_f32_16x16x32_f16 v[36:39], v[192:195], v[232:235], v[36:39]
	v_mfma_f32_16x16x32_f16 v[24:27], v[184:187], v[240:243], v[24:27]
	v_mfma_f32_16x16x32_f16 v[20:23], v[192:195], v[240:243], v[20:23]
	s_setprio 0
	s_setprio 1
	v_mfma_f32_16x16x32_f16 v[48:51], v[196:199], v[212:215], v[48:51]
	v_mfma_f32_16x16x32_f16 v[44:47], v[204:207], v[212:215], v[44:47]
	v_mfma_f32_16x16x32_f16 v[32:35], v[196:199], v[220:223], v[32:35]
	v_mfma_f32_16x16x32_f16 v[28:31], v[204:207], v[220:223], v[28:31]
	v_mfma_f32_16x16x32_f16 v[16:19], v[196:199], v[228:231], v[16:19]
	v_mfma_f32_16x16x32_f16 v[12:15], v[204:207], v[228:231], v[12:15]
	v_mfma_f32_16x16x32_f16 v[8:11], v[196:199], v[236:239], v[8:11]
	v_mfma_f32_16x16x32_f16 v[4:7], v[204:207], v[236:239], v[4:7]
	v_mfma_f32_16x16x32_f16 v[48:51], v[200:203], v[216:219], v[48:51]
	v_mfma_f32_16x16x32_f16 v[44:47], v[208:211], v[216:219], v[44:47]
	v_mfma_f32_16x16x32_f16 v[32:35], v[200:203], v[224:227], v[32:35]
	v_mfma_f32_16x16x32_f16 v[28:31], v[208:211], v[224:227], v[28:31]
	v_mfma_f32_16x16x32_f16 v[16:19], v[200:203], v[232:235], v[16:19]
	v_mfma_f32_16x16x32_f16 v[12:15], v[208:211], v[232:235], v[12:15]
	v_mfma_f32_16x16x32_f16 v[8:11], v[200:203], v[240:243], v[8:11]
	v_mfma_f32_16x16x32_f16 v[4:7], v[208:211], v[240:243], v[4:7]
	s_setprio 0
	s_barrier
	s_add_i32 s21, s21, 2
	s_add_u32 s54, s54, 0x100
	s_addc_u32 s55, s55, 0
	s_add_u32 s19, s19, 0x100
	s_addc_u32 s20, s20, 0
	s_cmp_gt_u32 s21, 13
	s_cbranch_scc0 .LBB0_673
	s_and_b64 vcc, exec, s[44:45]
	s_cbranch_vccz .LBB0_676
	s_barrier
